# rw_chunk_prep head: all 16 LoRA weight tiles of a group loaded up front into spare registers, three previous-token rows loaded in one masked block (five fewer serialized round trips per group)
# speedup vs baseline: 1.0280x; 1.0091x over previous
; #define LAS __attribute__((address_space(3)))
; __device__ __forceinline__ f32x4 bf4(v2u u) { return (f32x4){bflo(u.x), bfhi(u.x), bflo(u.y), bfhi(u.y)}; }
; #define MFMA32(a, b, c) __builtin_amdgcn_mfma_f32_16x16x32_bf16(a, b, c, 0, 0, 0)
; __device__ __forceinline__ void rw_chunk_prep(const Args& a, int head, int tc0, const LAS bf16* TDr, const LAS bf16* DAr, LAS unsigned char* lw_, int lane) {
;     ...
;     {   bf16x8 atd[2], ada[2];
; #pragma unroll
;         for (int kk = 0; kk < 2; ++kk) { atd[kk] = *(const LAS bf16x8*)(TDr + j * 64 + kk * 32 + kg * 8); ada[kk] = *(const LAS bf16x8*)(DAr + j * 64 + kk * 32 + kg * 8); }
; #pragma unroll
;         for (int cb = 0; cb < 4; ++cb) { accw[cb] = (f32x4){0.f, 0.f, 0.f, 0.f}; acca[cb] = (f32x4){0.f, 0.f, 0.f, 0.f};
; #pragma unroll
;             for (int kk = 0; kk < 2; ++kk) { const bf16x8 bw = *(const bf16x8*)(W2t + (size_t)(cbase + cb) * 64 + kk * 32 + kg * 8), ba = *(const bf16x8*)(A2t + (size_t)(cbase + cb) * 64 + kk * 32 + kg * 8);
;                 accw[cb] = MFMA32(atd[kk], bw, accw[cb]); acca[cb] = MFMA32(ada[kk], ba, acca[cb]); } }
;     }
;     const f32x4 w0 = ld4(a.in[9] + cbase), a0 = ld4(a.in[11] + cbase), kkw = ld4(a.in[13] + cbase), kaw = ld4(a.in[14] + cbase), rkw = ld4(a.in[15] + cbase);
;     const f32x4 mur = ld4(a.in[4] + cbase), muk = ld4(a.in[5] + cbase), muv = ld4(a.in[6] + cbase);
;     float* RK = (float*)(ws + WS_RK);
;     f32x4 rr[4], km[4], av[4], bv[4], lw[4], vv[4];
;     {   const int tt0 = tc0 + 4 * rg; const f32x4 zero = {0.f, 0.f, 0.f, 0.f};
;         f32x4 pr = tt0 > 0 ? bf4(*(const v2u*)(ZA + (size_t)(tt0 - 1) * 3072 + cbase)) : zero;
;         f32x4 pk = tt0 > 0 ? bf4(*(const v2u*)(ZA + (size_t)(tt0 - 1) * 3072 + 1024 + cbase)) : zero;
;         f32x4 pv = tt0 > 0 ? bf4(*(const v2u*)(ZA + (size_t)(tt0 - 1) * 3072 + 2048 + cbase)) : zero;
.LBB0_329:
	s_lshr_b32 s0, s59, 1
	s_add_i32 s0, s0, s34
	s_and_b32 s2, s58, 16
	v_lshl_add_u32 v4, s2, 7, v155
	v_lshl_or_b32 v66, s0, 6, v154
	ds_read_b128 v[0:3], v4
	ds_read_b128 v[16:19], v4 offset:4096
	ds_read_b128 v[20:23], v4 offset:64
	ds_read_b128 v[36:39], v4 offset:4160
	v_lshlrev_b64 v[4:5], 7, v[66:67]
	v_lshl_add_u64 v[12:13], v[74:75], 0, v[4:5]
	v_lshl_add_u64 v[24:25], v[76:77], 0, v[4:5]
	global_load_dwordx4 v[4:7], v[12:13], off
	global_load_dwordx4 v[8:11], v[24:25], off
	global_load_dwordx4 v[12:15], v[12:13], off offset:64
	global_load_dwordx4 v[24:27], v[24:25], off offset:64
	v_or_b32_e32 v214, 1, v66
	v_mov_b32_e32 v215, v67
	v_lshlrev_b64 v[214:215], 7, v[214:215]
	v_lshl_add_u64 v[218:219], v[76:77], 0, v[214:215]
	v_lshl_add_u64 v[214:215], v[74:75], 0, v[214:215]
	global_load_dwordx4 v[206:209], v[214:215], off
	global_load_dwordx4 v[210:213], v[218:219], off
	global_load_dwordx4 v[214:217], v[214:215], off offset:64
	global_load_dwordx4 v[218:221], v[218:219], off offset:64
	v_or_b32_e32 v230, 2, v66
	v_mov_b32_e32 v231, v67
	v_lshlrev_b64 v[230:231], 7, v[230:231]
	v_lshl_add_u64 v[234:235], v[76:77], 0, v[230:231]
	v_lshl_add_u64 v[230:231], v[74:75], 0, v[230:231]
	global_load_dwordx4 v[222:225], v[230:231], off
	global_load_dwordx4 v[226:229], v[234:235], off
	global_load_dwordx4 v[230:233], v[230:231], off offset:64
	global_load_dwordx4 v[234:237], v[234:235], off offset:64
	v_or_b32_e32 v246, 3, v66
	v_mov_b32_e32 v247, v67
	v_lshlrev_b64 v[246:247], 7, v[246:247]
	v_lshl_add_u64 v[250:251], v[76:77], 0, v[246:247]
	v_lshl_add_u64 v[246:247], v[74:75], 0, v[246:247]
	global_load_dwordx4 v[238:241], v[246:247], off
	global_load_dwordx4 v[242:245], v[250:251], off
	global_load_dwordx4 v[246:249], v[246:247], off offset:64
	global_load_dwordx4 v[250:253], v[250:251], off offset:64
	s_or_b32 s60, s2, s57
	v_add_u32_e32 v106, s60, v157
	v_cmp_lt_i32_e32 vcc, 0, v106
	v_mov_b32_e32 v186, 0
	v_add_u32_e32 v96, -1, v106
	v_mov_b32_e32 v98, 0
	v_mov_b32_e32 v100, 0
	v_mov_b32_e32 v99, 0
	v_mov_b32_e32 v101, 0
	s_waitcnt vmcnt(15) lgkmcnt(3)
	v_mfma_f32_16x16x32_bf16 v[4:7], v[0:3], v[4:7], 0
	s_waitcnt vmcnt(14) lgkmcnt(2)
	v_mfma_f32_16x16x32_bf16 v[8:11], v[16:19], v[8:11], 0
	s_waitcnt vmcnt(12) lgkmcnt(0)
	v_mfma_f32_16x16x32_bf16 v[24:27], v[36:39], v[24:27], v[8:11]
	v_mfma_f32_16x16x32_bf16 v[4:7], v[20:23], v[12:15], v[4:7]
	s_nop 4
	s_waitcnt vmcnt(11)
	v_mfma_f32_16x16x32_bf16 v[8:11], v[0:3], v[206:209], 0
	s_waitcnt vmcnt(10)
	v_mfma_f32_16x16x32_bf16 v[12:15], v[16:19], v[210:213], 0
	s_waitcnt vmcnt(9)
	v_mfma_f32_16x16x32_bf16 v[8:11], v[20:23], v[214:217], v[8:11]
	s_waitcnt vmcnt(8)
	v_mfma_f32_16x16x32_bf16 v[28:31], v[36:39], v[218:221], v[12:15]
	s_nop 3
	s_waitcnt vmcnt(7)
	v_mfma_f32_16x16x32_bf16 v[12:15], v[0:3], v[222:225], 0
	s_waitcnt vmcnt(6)
	v_mfma_f32_16x16x32_bf16 v[32:35], v[16:19], v[226:229], 0
	s_waitcnt vmcnt(5)
	v_mfma_f32_16x16x32_bf16 v[12:15], v[20:23], v[230:233], v[12:15]
	s_waitcnt vmcnt(4)
	v_mfma_f32_16x16x32_bf16 v[32:35], v[36:39], v[234:237], v[32:35]
	s_waitcnt vmcnt(3)
	v_mfma_f32_16x16x32_bf16 v[0:3], v[0:3], v[238:241], 0
	s_waitcnt vmcnt(2)
	v_mfma_f32_16x16x32_bf16 v[40:43], v[16:19], v[242:245], 0
	s_waitcnt vmcnt(1)
	v_mfma_f32_16x16x32_bf16 v[16:19], v[20:23], v[246:249], v[0:3]
	s_nop 2
	v_lshlrev_b64 v[0:1], 2, v[66:67]
	v_lshl_add_u64 v[2:3], s[38:39], 0, v[0:1]
	global_load_dwordx4 v[20:23], v[2:3], off
	v_lshl_add_u64 v[2:3], s[42:43], 0, v[0:1]
	global_load_dwordx4 v[60:63], v[2:3], off
	v_lshl_add_u64 v[2:3], s[46:47], 0, v[0:1]
	s_waitcnt vmcnt(2)
	v_mfma_f32_16x16x32_bf16 v[56:59], v[36:39], v[250:253], v[40:43]
	global_load_dwordx4 v[36:39], v[2:3], off
	v_lshl_add_u64 v[2:3], s[48:49], 0, v[0:1]
	global_load_dwordx4 v[52:55], v[2:3], off
	v_lshl_add_u64 v[2:3], s[50:51], 0, v[0:1]
	global_load_dwordx4 v[40:43], v[2:3], off
	v_lshl_add_u64 v[2:3], s[76:77], 0, v[0:1]
	global_load_dwordx4 v[44:47], v[2:3], off
	v_lshl_add_u64 v[2:3], s[78:79], 0, v[0:1]
	v_lshl_add_u64 v[0:1], s[80:81], 0, v[0:1]
	global_load_dwordx4 v[48:51], v[2:3], off
	v_lshlrev_b32_e32 v66, 1, v66
	global_load_dwordx4 v[0:3], v[0:1], off
	v_mov_b32_e32 v102, 0
	v_mov_b32_e32 v103, 0
	v_mov_b32_e32 v104, 0
	v_mov_b32_e32 v105, 0
	v_mov_b32_e32 v188, 0
	v_mov_b32_e32 v187, 0
	v_mov_b32_e32 v189, 0
	s_and_saveexec_b64 s[2:3], vcc
	v_mov_b64_e32 v[108:109], s[72:73]
	v_mad_u64_u32 v[108:109], s[26:27], v96, s44, v[108:109]
	v_lshl_add_u64 v[108:109], v[108:109], 0, v[66:67]
	global_load_dwordx2 v[100:101], v[108:109], off
	global_load_dwordx2 v[104:105], v[108:109], off offset:2048
	v_add_co_u32_e32 v108, vcc, 0x1000, v108
	s_nop 1
	v_addc_co_u32_e32 v109, vcc, 0, v109, vcc
	global_load_dwordx2 v[96:97], v[108:109], off
	s_waitcnt vmcnt(0)
	v_lshlrev_b32_e32 v98, 16, v100
	v_and_b32_e32 v100, 0xffff0000, v100
	v_lshlrev_b32_e32 v99, 16, v101
	v_and_b32_e32 v101, 0xffff0000, v101
	v_lshlrev_b32_e32 v102, 16, v104
	v_and_b32_e32 v103, 0xffff0000, v104
	v_lshlrev_b32_e32 v104, 16, v105
	v_and_b32_e32 v105, 0xffff0000, v105
	v_lshlrev_b32_e32 v186, 16, v96
	v_and_b32_e32 v188, 0xffff0000, v96
	v_lshlrev_b32_e32 v187, 16, v97
	v_and_b32_e32 v189, 0xffff0000, v97
